# placement trial: all code after the prologue shifted by 32 bytes (eight s_nop 0 before the layer loop); otherwise identical to the previous best
# speedup vs baseline: 1.0076x; 1.0018x over previous
; #define LAS __attribute__((address_space(3)))
; #define LANE_ASM(l_) asm volatile("v_mbcnt_lo_u32_b32 %0, -1, 0\n\tv_mbcnt_hi_u32_b32 %0, -1, %0" : "=v"(l_) :: "memory")
;     __device__ __forceinline__ unsigned char* ws() const { return (unsigned char*)(__attribute__((address_space(1))) unsigned char*)ld64(25); }
; #define GRID_SYNC_CG() do { asm volatile("s_waitcnt vmcnt(0) lgkmcnt(0)" ::: "memory"); grid.sync(); __builtin_amdgcn_fence(__ATOMIC_ACQUIRE, "agent"); asm volatile("s_waitcnt vmcnt(0)" ::: "memory"); } while (0)
; __global__ void __launch_bounds__(NTHREADS, 2) mega_fwd(Args a_unused) {
;     ...
;     Ctx a{lds};
;     prologue(a, lds, wave_s);
;     GRID_SYNC_CG();
;     { int l_; LANE_ASM(l_); (void)xcd_barrier_post((unsigned*)(a.ws() + WS_XBAR), (volatile LAS unsigned*)(lds + PTAB_OFF + 256), wave_s == 0 && l_ == 0); }
;     _Pragma("unroll") for (int layer = 0; layer < 4; ++layer) {
;         if (layer == 0) rowpass(a, true, false, 0, 0, 0, true, 6, 0, 1024, 0, layer, wave_s);
;         else rowpass(a, false, true, 9, layer - 1, 5120 - NB * 6144, true, 6, layer, 1024, 0, layer, wave_s);
.LBB0_104:
	s_or_b64 exec, exec, s[0:1]
	s_bfe_u32 s47, s3, 0x20006
	s_lshl_b32 s0, s47, 14
	s_add_i32 s0, s0, 0
	v_writelane_b32 v255, s0, 4
	s_lshl_b32 s0, s47, 5
	v_writelane_b32 v255, s0, 5
	s_lshr_b32 s2, s3, 8
	v_readlane_b32 s4, v255, 0
	s_lshl_b32 s1, s4, 2
	s_add_i32 s1, s1, 0
	s_lshl_b32 s0, s2, 6
	s_add_i32 s1, s1, 0x16800
	s_cmpk_lt_u32 s3, 0x100
	s_cselect_b64 s[14:15], -1, 0
	s_cmpk_gt_u32 s3, 0xff
	v_writelane_b32 v255, s1, 6
	s_cselect_b64 s[6:7], -1, 0
	v_writelane_b32 v255, s6, 7
	s_cmp_eq_u32 s2, 1
	s_mul_i32 s9, s63, s62
	v_writelane_b32 v255, s7, 8
	v_writelane_b32 v255, s2, 9
	s_cselect_b64 s[6:7], -1, 0
	v_writelane_b32 v255, s6, 10
	s_lshr_b32 s1, s3, 7
	s_lshl_b32 s56, s0, 1
	v_writelane_b32 v255, s7, 11
	v_writelane_b32 v255, s1, 12
	s_lshl_b32 s1, s4, 5
	s_and_b32 s2, s1, 32
	v_writelane_b32 v255, s2, 13
	s_lshl_b32 s2, s4, 9
	s_ashr_i32 s3, s2, 31
	v_writelane_b32 v255, s2, 14
	s_and_b32 s1, s1, 0x60
	s_add_i32 s0, 0, 0x16810
	v_writelane_b32 v255, s3, 15
	s_addk_i32 s2, 0xf800
	s_mov_b32 s3, s11
	v_writelane_b32 v255, s2, 16
	s_mul_i32 s9, s9, s18
	s_mov_b32 s55, 0xffff0000
	v_writelane_b32 v255, s3, 17
	v_writelane_b32 v255, s1, 18
	s_lshl_b32 s1, s4, 11
	v_writelane_b32 v255, s1, 19
	s_and_b32 s1, s1, 0x7fffe000
	s_add_i32 s1, s1, 0
	v_writelane_b32 v255, s1, 20
	s_lshl_b32 s1, s4, 3
	s_and_b32 s54, s1, 0x1fffffe0
	s_add_i32 s1, 0, 0x20048
	v_writelane_b32 v255, s1, 21
	s_add_i32 s1, 0, 0x20030
	v_writelane_b32 v255, s1, 22
	s_add_i32 s1, 0, 0x200c0
	v_writelane_b32 v255, s1, 23
	s_add_i32 s1, 0, 0x20000
	v_writelane_b32 v255, s1, 24
	s_add_i32 s1, 0, 0x20100
	v_writelane_b32 v255, s1, 25
	s_add_i32 s1, 0, 0x20104
	v_writelane_b32 v255, s1, 26
	s_add_i32 s1, 0, 0x200a8
	v_writelane_b32 v255, s1, 27
	s_add_i32 s1, 0, 0x16820
	v_writelane_b32 v255, s1, 28
	v_writelane_b32 v255, s0, 29
	s_add_i32 s0, 0, 0x200a0
	v_writelane_b32 v255, s0, 30
	s_add_i32 s0, 0, 0x20088
	v_writelane_b32 v255, s0, 31
	s_add_i32 s0, 0, 0x20038
	v_writelane_b32 v255, s0, 32
	v_writelane_b32 v255, s85, 33
	s_mov_b32 s0, s62
	s_lshl_b32 s2, s4, 10
	v_writelane_b32 v255, s0, 34
	s_add_i32 s52, s2, 0
	v_mov_b32_e32 v196, 0x358637bd
	s_mov_b32 s3, 0xf800000
	v_mov_b32_e32 v197, 0x260
	s_movk_i32 s48, 0x7fff
	v_mov_b32_e32 v1, 0
	v_mov_b32_e32 v198, 0x1000
	v_mov_b32_e32 v199, 0x2000
	v_mov_b32_e32 v201, 1
	s_mov_b32 s19, 0x42800000
	v_mov_b32_e32 v177, 0x426c0000
	v_mov_b64_e32 v[178:179], 0xf00
	v_mov_b64_e32 v[180:181], 0xeff
	v_mov_b32_e32 v202, 0x42800000
	v_mov_b32_e32 v203, 0xf149f2ca
	v_mov_b32_e32 v204, 0x7f800000
	v_mov_b32_e32 v205, 0x80
	v_mov_b32_e32 v254, 0xf00
	v_mov_b32_e32 v200, 0x8000
	v_mov_b32_e32 v208, 0xf0000
	v_mov_b32_e32 v209, 0x800000
	v_mov_b32_e32 v210, 0xf000000
	v_bfrev_b32_e32 v211, 1
	v_mov_b64_e32 v[182:183], 0x500
	v_mov_b64_e32 v[184:185], 0x4ff
	v_mov_b64_e32 v[186:187], 0x13ff
	s_mov_b32 s53, 0xff61b1e6
	s_mov_b32 s22, 0x40c00000
	s_add_i32 s21, 0, 0x20070
	s_mov_b32 s33, 0x43000000
	s_movk_i32 s46, 0xa1
	s_mov_b32 s17, 0x40000
	s_mov_b32 s50, 0x48000
	s_mov_b32 s20, 0x50000
	s_mov_b32 s49, 0x58000
	s_mov_b64 s[60:61], 0x800
	s_mov_b64 s[64:65], 0x1000
	s_mov_b64 s[66:67], 0x40000
	s_mov_b64 s[68:69], 0x80
	s_mov_b64 s[70:71], 0x2000
	s_mov_b32 s76, 0x3e38aa3b
	s_mov_b64 s[78:79], 0x48000
	s_mov_b64 s[80:81], 0x50000
	s_mov_b64 s[82:83], 0x58000
	s_mov_b32 s84, s11
	v_writelane_b32 v255, s1, 35
	s_nop 0
	s_nop 0
	s_nop 0
	s_nop 0
	s_nop 0
	s_nop 0
	s_nop 0
	s_nop 0
	s_branch .LBB0_107
